# a32: back-edge rotation (7.11) in attention L and E loops: next-iteration address SALU / K-V prefetch loads issued before the tile barrier on the taken path
# baseline (speedup 1.0000x reference)
.Lmy_rotL_head:
	ds_read_b128 v[92:95], v91 offset:39936
	ds_read_b128 v[96:99], v91 offset:39968
	ds_read_b128 v[100:103], v91 offset:44544
	ds_read_b128 v[104:107], v91 offset:44576
	ds_read_b128 v[108:111], v91 offset:40000
	ds_read_b128 v[112:115], v91 offset:40032
	ds_read_b128 v[116:119], v91 offset:44608
	ds_read_b128 v[120:123], v91 offset:44640
	ds_read_b128 v[124:127], v173
	ds_read_b128 v[128:131], v173 offset:32
	ds_read_b128 v[132:135], v173 offset:6656
	ds_read_b128 v[136:139], v173 offset:6688
	ds_read_b128 v[140:143], v173 offset:64
	ds_read_b128 v[144:147], v173 offset:96
	ds_read_b128 v[148:151], v173 offset:6720
	ds_read_b128 v[152:155], v173 offset:6752
	ds_read_b128 v[156:159], v173 offset:128
	ds_read_b128 v[160:163], v173 offset:160
	ds_read_b128 v[164:167], v173 offset:6784
	ds_read_b128 v[174:177], v173 offset:6816
	s_mov_b32 s22, s44
	s_add_i32 s8, s8, 1
	v_exp_f32_e32 v184, v48
	v_exp_f32_e32 v185, v49
	v_exp_f32_e32 v186, v50
	v_exp_f32_e32 v187, v51
	v_exp_f32_e32 v188, v52
	v_exp_f32_e32 v189, v53
	v_exp_f32_e32 v190, v54
	v_exp_f32_e32 v191, v55
	v_exp_f32_e32 v91, v32
	v_exp_f32_e32 v173, v33
	v_exp_f32_e32 v178, v34
	v_exp_f32_e32 v179, v35
	v_cvt_pk_bf16_f32 v32, v184, v185
	v_cvt_pk_bf16_f32 v33, v186, v187
	v_cvt_pk_bf16_f32 v34, v188, v189
	v_cvt_pk_bf16_f32 v35, v190, v191
	v_exp_f32_e32 v192, v56
	v_exp_f32_e32 v193, v57
	s_waitcnt lgkmcnt(14)
	v_mfma_f32_32x32x16_bf16 v[16:31], v[92:95], v[32:35], v[16:31]
	v_exp_f32_e32 v194, v58
	v_exp_f32_e32 v195, v59
	v_exp_f32_e32 v196, v60
	v_exp_f32_e32 v197, v61
	v_exp_f32_e32 v198, v62
	v_exp_f32_e32 v199, v63
	v_exp_f32_e32 v180, v36
	v_mfma_f32_32x32x16_bf16 v[0:15], v[100:103], v[32:35], v[0:15]
	v_exp_f32_e32 v181, v37
	v_exp_f32_e32 v182, v38
	v_exp_f32_e32 v183, v39
	v_cvt_pk_bf16_f32 v32, v192, v193
	v_cvt_pk_bf16_f32 v33, v194, v195
	v_cvt_pk_bf16_f32 v34, v196, v197
	v_cvt_pk_bf16_f32 v35, v198, v199
	v_exp_f32_e32 v200, v40
	v_exp_f32_e32 v201, v41
	v_mfma_f32_32x32x16_bf16 v[16:31], v[96:99], v[32:35], v[16:31]
	v_exp_f32_e32 v202, v42
	v_exp_f32_e32 v203, v43
	v_exp_f32_e32 v204, v44
	v_exp_f32_e32 v205, v45
	v_exp_f32_e32 v206, v46
	v_exp_f32_e32 v207, v47
	v_cvt_pk_bf16_f32 v36, v91, v173
	v_mfma_f32_32x32x16_bf16 v[0:15], v[104:107], v[32:35], v[0:15]
	v_cvt_pk_bf16_f32 v37, v178, v179
	v_cvt_pk_bf16_f32 v38, v180, v181
	v_cvt_pk_bf16_f32 v39, v182, v183
	v_add_f32_e32 v208, v184, v88
	v_add_f32_e32 v208, v91, v208
	v_mfma_f32_32x32x16_bf16 v[16:31], v[108:111], v[36:39], v[16:31]
	s_waitcnt lgkmcnt(13)
	v_mfma_f32_32x32x16_bf16 v[0:15], v[116:119], v[36:39], v[0:15]
	v_cvt_pk_bf16_f32 v32, v200, v201
	v_cvt_pk_bf16_f32 v33, v202, v203
	v_cvt_pk_bf16_f32 v34, v204, v205
	v_cvt_pk_bf16_f32 v35, v206, v207
	v_add_f32_e32 v208, v185, v208
	v_add_f32_e32 v208, v173, v208
	v_mfma_f32_32x32x16_bf16 v[16:31], v[112:115], v[32:35], v[16:31]
	s_waitcnt lgkmcnt(12)
	v_mfma_f32_32x32x16_bf16 v[0:15], v[120:123], v[32:35], v[0:15]
	s_setprio 1
	s_waitcnt lgkmcnt(11)
	v_mfma_f32_32x32x16_bf16 v[48:63], v[124:127], v[64:67], 0
	v_add_f32_e32 v208, v186, v208
	v_add_f32_e32 v208, v178, v208
	v_add_f32_e32 v208, v187, v208
	s_waitcnt lgkmcnt(9)
	v_mfma_f32_32x32x16_bf16 v[32:47], v[132:135], v[64:67], 0
	v_add_f32_e32 v208, v179, v208
	v_add_f32_e32 v208, v188, v208
	v_add_f32_e32 v208, v180, v208
	v_mfma_f32_32x32x16_bf16 v[48:63], v[128:131], v[68:71], v[48:63]
	v_add_f32_e32 v208, v189, v208
	v_add_f32_e32 v208, v181, v208
	v_add_f32_e32 v208, v190, v208
	s_waitcnt lgkmcnt(8)
	v_mfma_f32_32x32x16_bf16 v[32:47], v[136:139], v[68:71], v[32:47]
	v_add_f32_e32 v208, v182, v208
	v_add_f32_e32 v208, v191, v208
	v_add_f32_e32 v208, v183, v208
	s_waitcnt lgkmcnt(7)
	v_mfma_f32_32x32x16_bf16 v[48:63], v[140:143], v[72:75], v[48:63]
	v_add_f32_e32 v208, v192, v208
	v_add_f32_e32 v208, v200, v208
	s_waitcnt lgkmcnt(5)
	v_mfma_f32_32x32x16_bf16 v[32:47], v[148:151], v[72:75], v[32:47]
	v_add_f32_e32 v208, v193, v208
	v_add_f32_e32 v208, v201, v208
	v_mfma_f32_32x32x16_bf16 v[48:63], v[144:147], v[76:79], v[48:63]
	v_add_f32_e32 v208, v194, v208
	v_add_f32_e32 v208, v202, v208
	s_waitcnt lgkmcnt(4)
	v_mfma_f32_32x32x16_bf16 v[32:47], v[152:155], v[76:79], v[32:47]
	v_add_f32_e32 v208, v195, v208
	v_add_f32_e32 v208, v203, v208
	s_waitcnt lgkmcnt(3)
	v_mfma_f32_32x32x16_bf16 v[48:63], v[156:159], v[80:83], v[48:63]
	v_add_f32_e32 v208, v196, v208
	v_add_f32_e32 v208, v204, v208
	s_waitcnt lgkmcnt(1)
	v_mfma_f32_32x32x16_bf16 v[32:47], v[164:167], v[80:83], v[32:47]
	v_add_f32_e32 v208, v197, v208
	v_add_f32_e32 v208, v205, v208
	v_mfma_f32_32x32x16_bf16 v[48:63], v[160:163], v[84:87], v[48:63]
	v_add_f32_e32 v208, v198, v208
	v_add_f32_e32 v208, v206, v208
	s_waitcnt lgkmcnt(0)
	v_mfma_f32_32x32x16_bf16 v[32:47], v[174:177], v[84:87], v[32:47]
	v_add_f32_e32 v208, v199, v208
	v_add_f32_e32 v88, v207, v208
	s_setprio 0
	s_cmpk_lg_i32 s8, 0x7f
	s_mov_b32 s44, s9
	s_mov_b32 s9, s41
	s_cbranch_scc0 .Lmy_rotL_exit
	s_bitcmp1_b32 s8, 0
	s_mov_b32 s41, s22
	s_cselect_b32 s22, 0x2400, 0
	s_mul_i32 s45, s41, 0x3400
	v_add_u32_e32 v91, s22, v90
	v_add_u32_e32 v173, s45, v89
	s_barrier
	s_branch .Lmy_rotL_head
.Lmy_rotL_exit:
	s_barrier
	ds_read_b128 v[64:67], v90 offset:49152
	ds_read_b128 v[68:71], v90 offset:49184
	ds_read_b128 v[72:75], v90 offset:53760
	ds_read_b128 v[76:79], v90 offset:53792
	ds_read_b128 v[80:83], v90 offset:49216
	ds_read_b128 v[84:87], v90 offset:49248
	ds_read_b128 v[92:95], v90 offset:53824
	ds_read_b128 v[96:99], v90 offset:53856
	v_exp_f32_e32 v89, v48
	v_exp_f32_e32 v90, v49
	v_exp_f32_e32 v91, v50
	v_exp_f32_e32 v100, v51
	v_exp_f32_e32 v52, v52
	v_exp_f32_e32 v53, v53
	v_exp_f32_e32 v54, v54
	v_exp_f32_e32 v55, v55
	v_cvt_pk_bf16_f32 v48, v89, v90
	v_cvt_pk_bf16_f32 v49, v91, v100
	v_cvt_pk_bf16_f32 v50, v52, v53
	v_cvt_pk_bf16_f32 v51, v54, v55
	v_exp_f32_e32 v56, v56
	v_exp_f32_e32 v57, v57
	s_waitcnt lgkmcnt(7)
	v_mfma_f32_32x32x16_bf16 v[16:31], v[64:67], v[48:51], v[16:31]
	v_exp_f32_e32 v58, v58
	v_exp_f32_e32 v59, v59
	v_exp_f32_e32 v60, v60
	v_exp_f32_e32 v61, v61
	v_exp_f32_e32 v62, v62
	v_exp_f32_e32 v63, v63
	v_exp_f32_e32 v64, v32
	s_waitcnt lgkmcnt(5)
	v_mfma_f32_32x32x16_bf16 v[0:15], v[72:75], v[48:51], v[0:15]
	v_cvt_pk_bf16_f32 v48, v56, v57
	v_cvt_pk_bf16_f32 v49, v58, v59
	v_cvt_pk_bf16_f32 v50, v60, v61
	v_cvt_pk_bf16_f32 v51, v62, v63
	v_exp_f32_e32 v65, v33
	v_exp_f32_e32 v66, v34
	v_exp_f32_e32 v67, v35
	v_mfma_f32_32x32x16_bf16 v[16:31], v[68:71], v[48:51], v[16:31]
	v_exp_f32_e32 v36, v36
	v_exp_f32_e32 v37, v37
	v_exp_f32_e32 v38, v38
	v_exp_f32_e32 v39, v39
	v_cvt_pk_bf16_f32 v32, v64, v65
	v_cvt_pk_bf16_f32 v33, v66, v67
	v_cvt_pk_bf16_f32 v34, v36, v37
	s_waitcnt lgkmcnt(4)
	v_mfma_f32_32x32x16_bf16 v[0:15], v[76:79], v[48:51], v[0:15]
	v_cvt_pk_bf16_f32 v35, v38, v39
	v_add_f32_e32 v48, v88, v89
	v_add_f32_e32 v48, v64, v48
	v_exp_f32_e32 v40, v40
	v_exp_f32_e32 v41, v41
	v_exp_f32_e32 v42, v42
	v_exp_f32_e32 v43, v43
	s_waitcnt lgkmcnt(3)
	v_mfma_f32_32x32x16_bf16 v[16:31], v[80:83], v[32:35], v[16:31]
	v_exp_f32_e32 v44, v44
	v_exp_f32_e32 v45, v45
	v_exp_f32_e32 v46, v46
	v_exp_f32_e32 v47, v47
	v_add_f32_e32 v48, v90, v48
	v_add_f32_e32 v48, v65, v48
	v_add_f32_e32 v48, v91, v48
	s_waitcnt lgkmcnt(1)
	v_mfma_f32_32x32x16_bf16 v[0:15], v[92:95], v[32:35], v[0:15]
	v_add_f32_e32 v48, v66, v48
	v_cvt_pk_bf16_f32 v32, v40, v41
	v_cvt_pk_bf16_f32 v33, v42, v43
	v_cvt_pk_bf16_f32 v34, v44, v45
	v_cvt_pk_bf16_f32 v35, v46, v47
	v_add_f32_e32 v48, v100, v48
	s_mov_b64 s[44:45], 0
	v_mfma_f32_32x32x16_bf16 v[16:31], v[84:87], v[32:35], v[16:31]
	s_waitcnt lgkmcnt(0)
	s_barrier
	v_mfma_f32_32x32x16_bf16 v[0:15], v[96:99], v[32:35], v[0:15]
	v_add_f32_e32 v32, v67, v48
	v_add_f32_e32 v32, v52, v32
	v_add_f32_e32 v32, v36, v32
	v_add_f32_e32 v32, v53, v32
	v_add_f32_e32 v32, v37, v32
	v_add_f32_e32 v32, v54, v32
	v_add_f32_e32 v32, v38, v32
	v_add_f32_e32 v32, v55, v32
	v_add_f32_e32 v32, v39, v32
	v_add_f32_e32 v32, v56, v32
	v_add_f32_e32 v32, v40, v32
	v_add_f32_e32 v32, v57, v32
	v_add_f32_e32 v32, v41, v32
	v_add_f32_e32 v32, v58, v32
	v_add_f32_e32 v32, v42, v32
	v_add_f32_e32 v32, v59, v32
	v_add_f32_e32 v32, v43, v32
	v_add_f32_e32 v32, v60, v32
	v_add_f32_e32 v32, v44, v32
	v_add_f32_e32 v32, v61, v32
	v_add_f32_e32 v32, v45, v32
	v_add_f32_e32 v32, v62, v32
	v_add_f32_e32 v32, v46, v32
	v_add_f32_e32 v32, v63, v32
	v_add_f32_e32 v32, v47, v32
	v_mov_b32_e32 v33, v32
	s_nop 1
	v_permlane32_swap_b32_e32 v32, v33

.Lmy_rotE_head:
	s_setprio 1
	s_waitcnt vmcnt(10) lgkmcnt(11)
	v_mfma_f32_32x32x16_bf16 v[32:47], v[32:35], v[84:87], 0
	v_add_f32_e32 v220, v163, v159
	v_add_f32_e32 v220, v204, v220
	v_add_f32_e32 v220, v173, v220
	s_waitcnt lgkmcnt(9)
	v_mfma_f32_32x32x16_bf16 v[48:63], v[128:131], v[84:87], 0
	v_add_f32_e32 v220, v205, v220
	v_add_f32_e32 v220, v190, v220
	v_add_f32_e32 v220, v206, v220
	s_waitcnt vmcnt(9)
	v_mfma_f32_32x32x16_bf16 v[32:47], v[116:119], v[80:83], v[32:47]
	v_add_f32_e32 v220, v191, v220
	v_add_f32_e32 v220, v207, v220
	v_add_f32_e32 v220, v192, v220
	s_waitcnt lgkmcnt(8)
	v_mfma_f32_32x32x16_bf16 v[48:63], v[124:127], v[80:83], v[48:63]
	v_add_f32_e32 v220, v208, v220
	v_add_f32_e32 v220, v193, v220
	v_add_f32_e32 v220, v209, v220
	s_waitcnt vmcnt(8) lgkmcnt(7)
	v_mfma_f32_32x32x16_bf16 v[32:47], v[112:115], v[76:79], v[32:47]
	v_add_f32_e32 v220, v194, v220
	v_add_f32_e32 v220, v210, v220
	v_add_f32_e32 v220, v195, v220
	s_waitcnt lgkmcnt(5)
	v_mfma_f32_32x32x16_bf16 v[48:63], v[108:111], v[76:79], v[48:63]
	v_add_f32_e32 v220, v211, v220
	v_add_f32_e32 v220, v196, v220
	v_add_f32_e32 v220, v212, v220
	s_waitcnt vmcnt(7)
	v_mfma_f32_32x32x16_bf16 v[32:47], v[100:103], v[72:75], v[32:47]
	v_add_f32_e32 v220, v197, v220
	v_add_f32_e32 v220, v213, v220
	v_add_f32_e32 v220, v198, v220
	s_waitcnt lgkmcnt(4)
	v_mfma_f32_32x32x16_bf16 v[48:63], v[104:107], v[72:75], v[48:63]
	v_add_f32_e32 v220, v214, v220
	v_add_f32_e32 v220, v199, v220
	v_add_f32_e32 v220, v215, v220
	s_waitcnt vmcnt(6) lgkmcnt(3)
	v_mfma_f32_32x32x16_bf16 v[32:47], v[92:95], v[68:71], v[32:47]
	v_add_f32_e32 v220, v200, v220
	v_add_f32_e32 v220, v216, v220
	s_waitcnt lgkmcnt(1)
	v_mfma_f32_32x32x16_bf16 v[48:63], v[120:123], v[68:71], v[48:63]
	v_add_f32_e32 v220, v201, v220
	v_add_f32_e32 v220, v217, v220
	s_waitcnt vmcnt(5)
	v_mfma_f32_32x32x16_bf16 v[32:47], v[88:91], v[64:67], v[32:47]
	v_add_f32_e32 v220, v202, v220
	v_add_f32_e32 v220, v218, v220
	s_waitcnt lgkmcnt(0)
	v_mfma_f32_32x32x16_bf16 v[48:63], v[96:99], v[64:67], v[48:63]
	v_add_f32_e32 v220, v203, v220
	v_add_f32_e32 v159, v219, v220
	s_setprio 0
	s_mul_i32 s43, s44, 0x2400
	v_add_u32_e32 v100, s43, v157
	ds_read_b128 v[88:91], v100 offset:39936
	ds_read_b128 v[96:99], v100 offset:39968
	ds_read_b128 v[92:95], v100 offset:44544
	ds_read_b128 v[164:167], v100 offset:44576
	ds_read_b128 v[174:177], v100 offset:40000
	ds_read_b128 v[178:181], v100 offset:40032
	ds_read_b128 v[182:185], v100 offset:44608
	ds_read_b128 v[186:189], v100 offset:44640
	v_exp_f32_e32 v163, v32
	v_exp_f32_e32 v173, v33
	v_exp_f32_e32 v190, v34
	v_exp_f32_e32 v191, v35
	v_exp_f32_e32 v192, v36
	v_exp_f32_e32 v193, v37
	v_exp_f32_e32 v194, v38
	v_exp_f32_e32 v195, v39
	v_cvt_pk_bf16_f32 v36, v163, v173
	v_cvt_pk_bf16_f32 v37, v190, v191
	v_cvt_pk_bf16_f32 v38, v192, v193
	v_cvt_pk_bf16_f32 v39, v194, v195
	v_exp_f32_e32 v196, v40
	v_exp_f32_e32 v197, v41
	s_waitcnt lgkmcnt(7)
	v_mfma_f32_32x32x16_bf16 v[16:31], v[88:91], v[36:39], v[16:31]
	v_exp_f32_e32 v198, v42
	v_exp_f32_e32 v199, v43
	v_exp_f32_e32 v200, v44
	v_exp_f32_e32 v201, v45
	v_exp_f32_e32 v202, v46
	v_exp_f32_e32 v203, v47
	v_exp_f32_e32 v204, v48
	s_waitcnt lgkmcnt(5)
	v_mfma_f32_32x32x16_bf16 v[0:15], v[92:95], v[36:39], v[0:15]
	v_exp_f32_e32 v205, v49
	s_mul_i32 s43, s22, 0x3400
	v_add_u32_e32 v40, s43, v158
	v_cvt_pk_bf16_f32 v36, v196, v197
	v_cvt_pk_bf16_f32 v37, v198, v199
	v_cvt_pk_bf16_f32 v38, v200, v201
	v_cvt_pk_bf16_f32 v39, v202, v203
	v_exp_f32_e32 v206, v50
	ds_read_b128 v[32:35], v40
	ds_read_b128 v[116:119], v40 offset:32
	ds_read_b128 v[128:131], v40 offset:6656
	ds_read_b128 v[124:127], v40 offset:6688
	ds_read_b128 v[108:111], v40 offset:6720
	ds_read_b128 v[112:115], v40 offset:64
	ds_read_b128 v[100:103], v40 offset:96
	ds_read_b128 v[104:107], v40 offset:6752
	ds_read_b128 v[92:95], v40 offset:128
	ds_read_b128 v[88:91], v40 offset:160
	v_mfma_f32_32x32x16_bf16 v[16:31], v[96:99], v[36:39], v[16:31]
	ds_read_b128 v[120:123], v40 offset:6784
	ds_read_b128 v[96:99], v40 offset:6816
	v_cvt_pk_bf16_f32 v40, v204, v205
	v_exp_f32_e32 v207, v51
	s_waitcnt lgkmcnt(14)
	v_mfma_f32_32x32x16_bf16 v[0:15], v[164:167], v[36:39], v[0:15]
	v_exp_f32_e32 v208, v52
	v_exp_f32_e32 v209, v53
	v_exp_f32_e32 v210, v54
	v_exp_f32_e32 v211, v55
	v_cvt_pk_bf16_f32 v41, v206, v207
	v_cvt_pk_bf16_f32 v42, v208, v209
	v_cvt_pk_bf16_f32 v43, v210, v211
	v_exp_f32_e32 v212, v56
	v_exp_f32_e32 v213, v57
	v_mfma_f32_32x32x16_bf16 v[16:31], v[174:177], v[40:43], v[16:31]
	v_exp_f32_e32 v214, v58
	v_exp_f32_e32 v215, v59
	v_exp_f32_e32 v216, v60
	v_exp_f32_e32 v217, v61
	v_exp_f32_e32 v218, v62
	v_exp_f32_e32 v219, v63
	s_waitcnt lgkmcnt(13)
	v_mfma_f32_32x32x16_bf16 v[0:15], v[182:185], v[40:43], v[0:15]
	v_cvt_pk_bf16_f32 v36, v212, v213
	v_cvt_pk_bf16_f32 v37, v214, v215
	v_cvt_pk_bf16_f32 v38, v216, v217
	v_cvt_pk_bf16_f32 v39, v218, v219
	s_nop 1
	v_mfma_f32_32x32x16_bf16 v[16:31], v[178:181], v[36:39], v[16:31]
	s_waitcnt lgkmcnt(12)
	v_mfma_f32_32x32x16_bf16 v[0:15], v[186:189], v[36:39], v[0:15]
	s_mul_i32 s43, s59, 0x3400
	s_xor_b32 s44, s44, 1
	s_addk_i32 s9, 0x2000
	s_mov_b32 s59, s42
	s_mov_b32 s42, s22
	s_add_i32 s22, s43, 0
	s_mulk_i32 s44, 0x2400
	v_add_u32_e32 v38, s22, v160
	s_cmpk_lg_i32 s41, 0x7e
	v_add_u32_e32 v36, s22, v162
	v_add_u32_e32 v37, s22, v161
	v_add_u32_e32 v39, s44, v156
	s_waitcnt vmcnt(4)
	ds_write_b128 v38, v[140:143]
	s_waitcnt vmcnt(1)
	ds_write_b128 v37, v[148:151]
	ds_write_b128 v36, v[144:147]
	ds_write_b16 v39, v136 offset:39936
	ds_write_b16_d16_hi v39, v136 offset:40080
	ds_write_b16 v39, v137 offset:40224
	ds_write_b16_d16_hi v39, v137 offset:40368
	ds_write_b16 v39, v138 offset:40512
	ds_write_b16_d16_hi v39, v138 offset:40656
	ds_write_b16 v39, v139 offset:40800
	ds_write_b16_d16_hi v39, v139 offset:40944
	s_waitcnt vmcnt(0)
	ds_write_b16 v39, v132 offset:44544
	ds_write_b16_d16_hi v39, v132 offset:44688
	ds_write_b16 v39, v133 offset:44832
	ds_write_b16_d16_hi v39, v133 offset:44976
	ds_write_b16 v39, v134 offset:45120
	ds_write_b16_d16_hi v39, v134 offset:45264
	ds_write_b16 v39, v135 offset:45408
	ds_write_b16_d16_hi v39, v135 offset:45552
	s_waitcnt lgkmcnt(0)
	s_cbranch_scc0 .Lmy_rotE_exit
	s_add_i32 s22, s8, s41
	s_and_b32 s22, s22, 0x7f
	s_mulk_i32 s22, 0x3000
	v_lshl_add_u64 v[36:37], v[154:155], 0, s[22:23]
	global_load_dwordx4 v[140:143], v[36:37], off
	v_add_co_u32_e32 v36, vcc, s54, v36
	s_and_b32 s22, s9, 0xfe000
	s_nop 0
	v_addc_co_u32_e32 v37, vcc, 0, v37, vcc
	v_lshl_add_u64 v[38:39], v[152:153], 0, s[22:23]
	global_load_dwordx4 v[144:147], v[36:37], off
	global_load_dwordx4 v[136:139], v[38:39], off
	global_load_dwordx4 v[148:151], v[36:37], off offset:-4096
	global_load_dwordx4 v[132:135], v[38:39], off offset:64
	s_mov_b32 s22, s39
	s_mov_b32 s39, s59
	s_and_b32 s44, s41, 1
	s_add_i32 s41, s41, 1
	s_barrier
	s_branch .Lmy_rotE_head
.Lmy_rotE_exit:
	s_barrier
	s_add_i32 s8, s40, 0xfe000
	s_and_b32 s22, s8, 0xfe000
	v_lshl_add_u64 v[36:37], v[152:153], 0, s[22:23]
	global_load_dwordx4 v[132:135], v[36:37], off
	global_load_dwordx4 v[136:139], v[36:37], off offset:64
	s_setprio 1
	v_mfma_f32_32x32x16_bf16 v[48:63], v[32:35], v[84:87], 0
	v_add_f32_e32 v220, v163, v159
	v_add_f32_e32 v220, v204, v220
	v_add_f32_e32 v220, v173, v220
	v_mfma_f32_32x32x16_bf16 v[32:47], v[128:131], v[84:87], 0
	v_add_f32_e32 v220, v205, v220
	v_add_f32_e32 v220, v190, v220
	v_add_f32_e32 v220, v206, v220
	v_mfma_f32_32x32x16_bf16 v[32:47], v[124:127], v[80:83], v[32:47]
	v_add_f32_e32 v220, v191, v220
	v_add_f32_e32 v220, v207, v220
	v_add_f32_e32 v220, v192, v220
	v_mfma_f32_32x32x16_bf16 v[48:63], v[116:119], v[80:83], v[48:63]
	v_add_f32_e32 v220, v208, v220
	v_add_f32_e32 v220, v193, v220
	v_add_f32_e32 v220, v209, v220
	v_mfma_f32_32x32x16_bf16 v[32:47], v[108:111], v[76:79], v[32:47]
	v_add_f32_e32 v220, v194, v220
	v_add_f32_e32 v220, v210, v220
	v_add_f32_e32 v220, v195, v220
	v_mfma_f32_32x32x16_bf16 v[48:63], v[112:115], v[76:79], v[48:63]
	v_add_f32_e32 v220, v211, v220
	v_add_f32_e32 v220, v196, v220
	v_add_f32_e32 v220, v212, v220
	v_mfma_f32_32x32x16_bf16 v[32:47], v[104:107], v[72:75], v[32:47]
	v_add_f32_e32 v220, v197, v220
	v_add_f32_e32 v220, v213, v220
	v_add_f32_e32 v220, v198, v220
	v_mfma_f32_32x32x16_bf16 v[48:63], v[100:103], v[72:75], v[48:63]
	v_add_f32_e32 v220, v214, v220
	v_add_f32_e32 v220, v199, v220
	v_add_f32_e32 v220, v215, v220
	v_mfma_f32_32x32x16_bf16 v[32:47], v[120:123], v[68:71], v[32:47]
	v_add_f32_e32 v220, v200, v220
	v_add_f32_e32 v220, v216, v220
	v_mfma_f32_32x32x16_bf16 v[48:63], v[92:95], v[68:71], v[48:63]
	v_add_f32_e32 v220, v201, v220
	v_add_f32_e32 v220, v217, v220
	v_mfma_f32_32x32x16_bf16 v[32:47], v[96:99], v[64:67], v[32:47]
	v_add_f32_e32 v220, v202, v220
	v_add_f32_e32 v220, v218, v220
	v_mfma_f32_32x32x16_bf16 v[48:63], v[88:91], v[64:67], v[48:63]
	v_add_f32_e32 v220, v203, v220
	v_add_f32_e32 v159, v219, v220
	s_setprio 0
	ds_read_b128 v[88:91], v157 offset:39936
	ds_read_b128 v[92:95], v157 offset:39968
	ds_read_b128 v[96:99], v157 offset:44544
	ds_read_b128 v[100:103], v157 offset:44576
	ds_read_b128 v[104:107], v157 offset:40000
	ds_read_b128 v[108:111], v157 offset:40032
	ds_read_b128 v[112:115], v157 offset:44608
	ds_read_b128 v[116:119], v157 offset:44640
	s_nop 2
	v_exp_f32_e32 v140, v48
	v_exp_f32_e32 v141, v49
	v_exp_f32_e32 v142, v50
	v_exp_f32_e32 v143, v51
	v_exp_f32_e32 v52, v52
	v_exp_f32_e32 v53, v53
	v_exp_f32_e32 v54, v54
	v_exp_f32_e32 v55, v55
	v_cvt_pk_bf16_f32 v48, v140, v141
	v_cvt_pk_bf16_f32 v49, v142, v143
	v_cvt_pk_bf16_f32 v50, v52, v53
	v_cvt_pk_bf16_f32 v51, v54, v55
	v_exp_f32_e32 v56, v56
	v_exp_f32_e32 v57, v57
	s_waitcnt lgkmcnt(7)
	v_mfma_f32_32x32x16_bf16 v[16:31], v[88:91], v[48:51], v[16:31]
	v_exp_f32_e32 v58, v58
	v_exp_f32_e32 v59, v59
	v_exp_f32_e32 v60, v60
	v_exp_f32_e32 v61, v61
	v_exp_f32_e32 v62, v62
	v_exp_f32_e32 v63, v63
	v_exp_f32_e32 v144, v32
	s_waitcnt lgkmcnt(5)
	v_mfma_f32_32x32x16_bf16 v[0:15], v[96:99], v[48:51], v[0:15]
	v_cvt_pk_bf16_f32 v48, v56, v57
	v_cvt_pk_bf16_f32 v49, v58, v59
	v_cvt_pk_bf16_f32 v50, v60, v61
	v_cvt_pk_bf16_f32 v51, v62, v63
	v_exp_f32_e32 v145, v33
	v_exp_f32_e32 v146, v34
	v_exp_f32_e32 v147, v35
	v_mfma_f32_32x32x16_bf16 v[16:31], v[92:95], v[48:51], v[16:31]
	v_exp_f32_e32 v148, v36
	v_cvt_pk_bf16_f32 v32, v144, v145
	v_cvt_pk_bf16_f32 v33, v146, v147
	v_exp_f32_e32 v149, v41
	v_exp_f32_e32 v150, v42
	v_exp_f32_e32 v151, v43
	v_exp_f32_e32 v44, v44
	s_waitcnt lgkmcnt(4)
	v_mfma_f32_32x32x16_bf16 v[0:15], v[100:103], v[48:51], v[0:15]
	v_exp_f32_e32 v48, v37
	v_exp_f32_e32 v49, v38
	v_exp_f32_e32 v50, v39
	v_exp_f32_e32 v51, v40
	v_cvt_pk_bf16_f32 v34, v148, v48
	v_exp_f32_e32 v45, v45
	v_cvt_pk_bf16_f32 v35, v49, v50
	v_exp_f32_e32 v46, v46
	v_exp_f32_e32 v47, v47
	s_waitcnt lgkmcnt(3)
	v_mfma_f32_32x32x16_bf16 v[16:31], v[104:107], v[32:35], v[16:31]
	v_add_u32_e32 v128, s43, v158
	s_waitcnt lgkmcnt(1)
	v_mfma_f32_32x32x16_bf16 v[0:15], v[112:115], v[32:35], v[0:15]
	v_cvt_pk_bf16_f32 v32, v51, v149
	v_cvt_pk_bf16_f32 v33, v150, v151
	v_cvt_pk_bf16_f32 v34, v44, v45
	v_cvt_pk_bf16_f32 v35, v46, v47
	s_nop 1
	v_mfma_f32_32x32x16_bf16 v[16:31], v[108:111], v[32:35], v[16:31]
	ds_read_b128 v[36:39], v128
	ds_read_b128 v[88:91], v128 offset:32
	ds_read_b128 v[40:43], v128 offset:6656
	ds_read_b128 v[92:95], v128 offset:6688
	ds_read_b128 v[96:99], v128 offset:64
	ds_read_b128 v[100:103], v128 offset:96
	ds_read_b128 v[104:107], v128 offset:6720
	ds_read_b128 v[108:111], v128 offset:6752
	ds_read_b128 v[112:115], v128 offset:128
	ds_read_b128 v[120:123], v128 offset:160
	ds_read_b128 v[124:127], v128 offset:6784
	ds_read_b128 v[128:131], v128 offset:6816
	s_waitcnt lgkmcnt(12)
	v_mfma_f32_32x32x16_bf16 v[0:15], v[116:119], v[32:35], v[0:15]
	v_add_f32_e32 v32, v159, v140
	v_add_f32_e32 v32, v144, v32
	v_add_f32_e32 v32, v141, v32
	v_add_f32_e32 v32, v145, v32
	v_add_f32_e32 v32, v142, v32
	v_add_f32_e32 v32, v146, v32
	v_add_f32_e32 v32, v143, v32
	v_add_f32_e32 v32, v147, v32
	v_add_f32_e32 v32, v52, v32
	v_add_f32_e32 v32, v148, v32
	v_add_f32_e32 v32, v53, v32
	v_add_f32_e32 v32, v48, v32
	v_add_f32_e32 v32, v54, v32
	v_add_f32_e32 v32, v49, v32
	v_add_f32_e32 v32, v55, v32
	v_add_f32_e32 v32, v50, v32
	v_add_f32_e32 v32, v56, v32
	v_add_f32_e32 v32, v51, v32
	v_add_f32_e32 v32, v57, v32
	v_add_f32_e32 v32, v149, v32
	v_add_f32_e32 v32, v58, v32
	v_add_f32_e32 v32, v150, v32
	v_add_f32_e32 v32, v59, v32
	v_add_f32_e32 v32, v151, v32
	v_add_f32_e32 v32, v60, v32
	v_add_f32_e32 v32, v44, v32
	v_add_f32_e32 v32, v61, v32
	v_add_f32_e32 v32, v45, v32
	v_add_f32_e32 v32, v62, v32
	v_add_f32_e32 v32, v46, v32
	v_add_f32_e32 v32, v63, v32
	v_add_f32_e32 v116, v47, v32
	s_waitcnt vmcnt(1)
	ds_write_b16 v156, v132 offset:49152
	ds_write_b16_d16_hi v156, v132 offset:49296
	ds_write_b16 v156, v133 offset:49440
	ds_write_b16_d16_hi v156, v133 offset:49584
	ds_write_b16 v156, v134 offset:49728
	ds_write_b16_d16_hi v156, v134 offset:49872
	ds_write_b16 v156, v135 offset:50016
	ds_write_b16_d16_hi v156, v135 offset:50160
	s_waitcnt vmcnt(0)
	ds_write_b16 v156, v136 offset:53760
	ds_write_b16_d16_hi v156, v136 offset:53904
	ds_write_b16 v156, v137 offset:54048
	ds_write_b16_d16_hi v156, v137 offset:54192
	ds_write_b16 v156, v138 offset:54336
	ds_write_b16_d16_hi v156, v138 offset:54480
	ds_write_b16 v156, v139 offset:54624
	ds_write_b16_d16_hi v156, v139 offset:54768
	s_waitcnt lgkmcnt(0)
	s_barrier
	s_setprio 1
	v_mfma_f32_32x32x16_bf16 v[48:63], v[36:39], v[84:87], 0
	v_mfma_f32_32x32x16_bf16 v[32:47], v[40:43], v[84:87], 0
	v_mfma_f32_32x32x16_bf16 v[32:47], v[92:95], v[80:83], v[32:47]
	v_mfma_f32_32x32x16_bf16 v[48:63], v[88:91], v[80:83], v[48:63]
	v_mfma_f32_32x32x16_bf16 v[32:47], v[104:107], v[76:79], v[32:47]
	v_mfma_f32_32x32x16_bf16 v[48:63], v[96:99], v[76:79], v[48:63]
	v_mfma_f32_32x32x16_bf16 v[32:47], v[108:111], v[72:75], v[32:47]
	v_mfma_f32_32x32x16_bf16 v[48:63], v[100:103], v[72:75], v[48:63]
	v_mfma_f32_32x32x16_bf16 v[32:47], v[124:127], v[68:71], v[32:47]
	v_mfma_f32_32x32x16_bf16 v[48:63], v[112:115], v[68:71], v[48:63]
	v_mfma_f32_32x32x16_bf16 v[32:47], v[128:131], v[64:67], v[32:47]
	v_mfma_f32_32x32x16_bf16 v[48:63], v[120:123], v[64:67], v[48:63]
	s_setprio 0
	ds_read_b128 v[64:67], v157 offset:49152
	ds_read_b128 v[68:71], v157 offset:49184
	ds_read_b128 v[72:75], v157 offset:53760
	ds_read_b128 v[76:79], v157 offset:53792
	ds_read_b128 v[80:83], v157 offset:49216
	ds_read_b128 v[84:87], v157 offset:49248
	ds_read_b128 v[88:91], v157 offset:53824
	ds_read_b128 v[92:95], v157 offset:53856
	s_nop 2
	v_exp_f32_e32 v96, v48
	v_exp_f32_e32 v97, v49
	v_exp_f32_e32 v98, v50
	v_exp_f32_e32 v99, v51
	v_exp_f32_e32 v52, v52
	v_exp_f32_e32 v53, v53
	v_exp_f32_e32 v54, v54
	v_exp_f32_e32 v55, v55
	v_cvt_pk_bf16_f32 v48, v96, v97
	v_cvt_pk_bf16_f32 v49, v98, v99
	v_cvt_pk_bf16_f32 v50, v52, v53
	v_cvt_pk_bf16_f32 v51, v54, v55
	v_exp_f32_e32 v56, v56
	v_exp_f32_e32 v57, v57
	s_waitcnt lgkmcnt(7)
	v_mfma_f32_32x32x16_bf16 v[16:31], v[64:67], v[48:51], v[16:31]
	v_exp_f32_e32 v58, v58
	v_exp_f32_e32 v59, v59
	v_exp_f32_e32 v60, v60
	v_exp_f32_e32 v61, v61
	v_exp_f32_e32 v62, v62
	v_exp_f32_e32 v63, v63
	v_exp_f32_e32 v64, v32
	s_waitcnt lgkmcnt(5)
	v_mfma_f32_32x32x16_bf16 v[0:15], v[72:75], v[48:51], v[0:15]
	v_cvt_pk_bf16_f32 v48, v56, v57
	v_cvt_pk_bf16_f32 v49, v58, v59
	v_cvt_pk_bf16_f32 v50, v60, v61
	v_cvt_pk_bf16_f32 v51, v62, v63
	v_exp_f32_e32 v65, v33
	v_exp_f32_e32 v66, v34
	v_exp_f32_e32 v67, v35
	v_mfma_f32_32x32x16_bf16 v[16:31], v[68:71], v[48:51], v[16:31]
	v_exp_f32_e32 v36, v36
	v_exp_f32_e32 v37, v37
	v_exp_f32_e32 v38, v38
	v_exp_f32_e32 v39, v39
	v_cvt_pk_bf16_f32 v32, v64, v65
	v_cvt_pk_bf16_f32 v33, v66, v67
	v_cvt_pk_bf16_f32 v34, v36, v37
	s_waitcnt lgkmcnt(4)
	v_mfma_f32_32x32x16_bf16 v[0:15], v[76:79], v[48:51], v[0:15]
	v_cvt_pk_bf16_f32 v35, v38, v39
	v_add_f32_e32 v48, v116, v96
	v_add_f32_e32 v48, v64, v48
	v_exp_f32_e32 v40, v40
	v_exp_f32_e32 v41, v41
	v_exp_f32_e32 v42, v42
	v_exp_f32_e32 v43, v43
	s_waitcnt lgkmcnt(3)
	v_mfma_f32_32x32x16_bf16 v[16:31], v[80:83], v[32:35], v[16:31]
	v_exp_f32_e32 v44, v44
	v_exp_f32_e32 v45, v45
	v_exp_f32_e32 v46, v46
	v_exp_f32_e32 v47, v47
	v_add_f32_e32 v48, v97, v48
	v_add_f32_e32 v48, v65, v48
	v_add_f32_e32 v48, v98, v48
	s_waitcnt lgkmcnt(1)
	v_mfma_f32_32x32x16_bf16 v[0:15], v[88:91], v[32:35], v[0:15]
	v_add_f32_e32 v48, v66, v48
	v_cvt_pk_bf16_f32 v32, v40, v41
	v_cvt_pk_bf16_f32 v33, v42, v43
	v_cvt_pk_bf16_f32 v34, v44, v45
	v_cvt_pk_bf16_f32 v35, v46, v47
	v_add_f32_e32 v48, v99, v48
	s_waitcnt lgkmcnt(0)
	v_mfma_f32_32x32x16_bf16 v[16:31], v[84:87], v[32:35], v[16:31]
	s_barrier
	v_mfma_f32_32x32x16_bf16 v[0:15], v[92:95], v[32:35], v[0:15]
	v_add_f32_e32 v32, v67, v48
	v_add_f32_e32 v32, v52, v32
	v_add_f32_e32 v32, v36, v32
	v_add_f32_e32 v32, v53, v32
	v_add_f32_e32 v32, v37, v32
	v_add_f32_e32 v32, v54, v32
	v_add_f32_e32 v32, v38, v32
	v_add_f32_e32 v32, v55, v32
	v_add_f32_e32 v32, v39, v32
	v_add_f32_e32 v32, v56, v32
	v_add_f32_e32 v32, v40, v32
	v_add_f32_e32 v32, v57, v32
	v_add_f32_e32 v32, v41, v32
	v_add_f32_e32 v32, v58, v32
	v_add_f32_e32 v32, v42, v32
	v_add_f32_e32 v32, v59, v32
	v_add_f32_e32 v32, v43, v32
	v_add_f32_e32 v32, v60, v32
	v_add_f32_e32 v32, v44, v32
	v_add_f32_e32 v32, v61, v32
	v_add_f32_e32 v32, v45, v32
	v_add_f32_e32 v32, v62, v32
	v_add_f32_e32 v32, v46, v32
	v_add_f32_e32 v32, v63, v32
	v_add_f32_e32 v32, v47, v32
	v_mov_b32_e32 v33, v32
	s_nop 1
	v_permlane32_swap_b32_e32 v32, v33
	s_branch .LBB0_592
